# ff1 GEMM epilogue: loads issued in first-use order (row statistic, column vectors, remaining statistics) with counted waits at each first use
# baseline (speedup 1.0000x reference)
.LBB0_756:
	v_lshl_add_u32 v164, s4, 8, v168
	v_ashrrev_i32_e32 v165, 31, v164
	v_lshl_add_u64 v[160:161], v[164:165], 2, s[12:13]
	global_load_dword v177, v[160:161], off
	s_ashr_i32 s4, s4, 4
	s_ashr_i32 s5, s4, 31
	s_lshl_b64 s[4:5], s[4:5], 14
	v_lshl_or_b32 v162, s3, 8, v170
	s_add_u32 s4, s67, s4
	v_ashrrev_i32_e32 v163, 31, v162
	s_addc_u32 s5, s68, s5
	v_lshl_add_u64 v[88:89], v[162:163], 2, s[4:5]
	global_load_dwordx4 v[100:103], v[88:89], off
	global_load_dwordx4 v[96:99], v[88:89], off offset:16
	global_load_dwordx4 v[92:95], v[88:89], off offset:512
	s_nop 0
	global_load_dwordx4 v[88:91], v[88:89], off offset:528
	global_load_dword v230, v[160:161], off offset:64
	global_load_dword v231, v[160:161], off offset:128
	global_load_dword v232, v[160:161], off offset:192
	global_load_dword v233, v[160:161], off offset:512
	global_load_dword v234, v[160:161], off offset:576
	global_load_dword v235, v[160:161], off offset:640
	global_load_dword v236, v[160:161], off offset:704
	v_lshlrev_b64 v[166:167], 1, v[162:163]
	v_lshlrev_b64 v[178:179], 13, v[164:165]
	v_or_b32_e32 v176, 16, v164
	s_waitcnt vmcnt(11)
	v_fmamk_f32 v162, v177, 0x3a800000, v174
	v_mul_f32_e32 v163, 0x4f800000, v162
	v_cmp_gt_f32_e32 vcc, s75, v162
	v_ashrrev_i32_e32 v177, 31, v176
	s_nop 0
	v_cndmask_b32_e32 v165, v162, v163, vcc
	v_sqrt_f32_e32 v180, v165
	v_lshl_add_u64 v[162:163], s[22:23], 0, v[178:179]
	v_lshl_add_u64 v[162:163], v[162:163], 0, v[166:167]
	v_lshl_add_u64 v[178:179], v[176:177], 2, s[12:13]
	v_add_u32_e32 v181, -1, v180
	v_add_u32_e32 v182, 1, v180
	v_fma_f32 v183, -v181, v180, v165
	v_fma_f32 v184, -v182, v180, v165
	v_cmp_ge_f32_e64 s[4:5], 0, v183
	s_nop 1
	v_cndmask_b32_e64 v180, v180, v181, s[4:5]
	v_cmp_lt_f32_e64 s[4:5], 0, v184
	s_nop 1
	v_cndmask_b32_e64 v180, v180, v182, s[4:5]
	v_mul_f32_e32 v181, 0x37800000, v180
	v_cndmask_b32_e32 v180, v180, v181, vcc
	v_cmp_class_f32_e32 vcc, v165, v175
	s_nop 1
	v_cndmask_b32_e32 v165, v180, v165, vcc
	v_div_scale_f32 v180, s[4:5], v165, v165, 1.0
	v_rcp_f32_e32 v181, v180
	v_div_scale_f32 v182, vcc, 1.0, v165, 1.0
	v_fma_f32 v183, -v180, v181, 1.0
	v_fmac_f32_e32 v181, v183, v181
	v_mul_f32_e32 v183, v182, v181
	v_fma_f32 v184, -v180, v183, v182
	v_fmac_f32_e32 v183, v184, v181
	v_fma_f32 v180, -v180, v183, v182
	v_div_fmas_f32 v180, v180, v181, v183
	v_div_fixup_f32 v180, v180, v165, 1.0
	s_waitcnt vmcnt(7)
	v_pk_fma_f32 v[142:143], v[142:143], v[180:181], v[102:103] op_sel_hi:[1,0,1]
	v_pk_fma_f32 v[140:141], v[140:141], v[180:181], v[100:101] op_sel_hi:[1,0,1]
	v_pk_fma_f32 v[138:139], v[138:139], v[180:181], v[98:99] op_sel_hi:[1,0,1]
	v_pk_fma_f32 v[136:137], v[136:137], v[180:181], v[96:97] op_sel_hi:[1,0,1]
	v_pk_fma_f32 v[134:135], v[134:135], v[180:181], v[94:95] op_sel_hi:[1,0,1]
	v_pk_fma_f32 v[132:133], v[132:133], v[180:181], v[92:93] op_sel_hi:[1,0,1]
	v_pk_fma_f32 v[130:131], v[130:131], v[180:181], v[90:91] op_sel_hi:[1,0,1]
	v_pk_fma_f32 v[128:129], v[128:129], v[180:181], v[88:89] op_sel_hi:[1,0,1]
	v_max_f32_e32 v140, 0, v140
	v_max_f32_e32 v136, 0, v136
	v_max_f32_e32 v141, 0, v141
	v_max_f32_e32 v137, 0, v137
	v_max_f32_e32 v142, 0, v142
	v_max_f32_e32 v138, 0, v138
	v_max_f32_e32 v143, 0, v143
	v_max_f32_e32 v139, 0, v139
	v_max_f32_e32 v132, 0, v132
	v_max_f32_e32 v128, 0, v128
	v_max_f32_e32 v133, 0, v133
	v_max_f32_e32 v129, 0, v129
	v_max_f32_e32 v134, 0, v134
	v_max_f32_e32 v130, 0, v130
	v_max_f32_e32 v135, 0, v135
	v_max_f32_e32 v131, 0, v131
	v_pk_mul_f32 v[140:141], v[140:141], v[140:141]
	v_pk_mul_f32 v[136:137], v[136:137], v[136:137]
	v_pk_mul_f32 v[142:143], v[142:143], v[142:143]
	v_pk_mul_f32 v[138:139], v[138:139], v[138:139]
	v_pk_mul_f32 v[132:133], v[132:133], v[132:133]
	v_pk_mul_f32 v[180:181], v[128:129], v[128:129]
	v_pk_mul_f32 v[134:135], v[134:135], v[134:135]
	v_pk_mul_f32 v[182:183], v[130:131], v[130:131]
	v_cvt_pk_bf16_f32 v128, v140, v141
	v_cvt_pk_bf16_f32 v129, v142, v143
	v_cvt_pk_bf16_f32 v130, v136, v137
	v_cvt_pk_bf16_f32 v131, v138, v139
	v_cvt_pk_bf16_f32 v132, v132, v133
	v_cvt_pk_bf16_f32 v133, v134, v135
	v_cvt_pk_bf16_f32 v134, v180, v181
	v_cvt_pk_bf16_f32 v135, v182, v183
	global_store_dwordx4 v[162:163], v[128:131], off
	global_store_dwordx4 v[162:163], v[132:135], off offset:256
	s_nop 1
	s_waitcnt vmcnt(2)
	v_mov_b32_e32 v130, v230
	v_or_b32_e32 v128, 32, v164
	v_ashrrev_i32_e32 v129, 31, v128
	v_lshl_add_u64 v[132:133], v[128:129], 2, s[12:13]
	s_nop 0
	v_fmamk_f32 v130, v130, 0x3a800000, v174
	v_mul_f32_e32 v131, 0x4f800000, v130
	v_cmp_gt_f32_e32 vcc, s75, v130
	s_nop 1
	v_cndmask_b32_e32 v134, v130, v131, vcc
	v_sqrt_f32_e32 v135, v134
	v_lshlrev_b64 v[130:131], 13, v[176:177]
	v_lshl_add_u64 v[130:131], s[22:23], 0, v[130:131]
	v_lshl_add_u64 v[130:131], v[130:131], 0, v[166:167]
	v_add_u32_e32 v136, -1, v135
	v_add_u32_e32 v137, 1, v135
	v_fma_f32 v138, -v136, v135, v134
	v_fma_f32 v139, -v137, v135, v134
	v_cmp_ge_f32_e64 s[4:5], 0, v138
	s_nop 1
	v_cndmask_b32_e64 v135, v135, v136, s[4:5]
	v_cmp_lt_f32_e64 s[4:5], 0, v139
	s_nop 1
	v_cndmask_b32_e64 v135, v135, v137, s[4:5]
	v_mul_f32_e32 v136, 0x37800000, v135
	v_cndmask_b32_e32 v135, v135, v136, vcc
	v_cmp_class_f32_e32 vcc, v134, v175
	s_nop 1
	v_cndmask_b32_e32 v134, v135, v134, vcc
	v_div_scale_f32 v135, s[4:5], v134, v134, 1.0
	v_rcp_f32_e32 v136, v135
	v_div_scale_f32 v137, vcc, 1.0, v134, 1.0
	v_fma_f32 v138, -v135, v136, 1.0
	v_fmac_f32_e32 v136, v138, v136
	v_mul_f32_e32 v138, v137, v136
	v_fma_f32 v139, -v135, v138, v137
	v_fmac_f32_e32 v138, v139, v136
	v_fma_f32 v135, -v135, v138, v137
	v_div_fmas_f32 v135, v135, v136, v138
	v_div_fixup_f32 v134, v135, v134, 1.0
	v_pk_fma_f32 v[126:127], v[126:127], v[134:135], v[102:103] op_sel_hi:[1,0,1]
	v_pk_fma_f32 v[124:125], v[124:125], v[134:135], v[100:101] op_sel_hi:[1,0,1]
	v_pk_fma_f32 v[122:123], v[122:123], v[134:135], v[98:99] op_sel_hi:[1,0,1]
	v_pk_fma_f32 v[120:121], v[120:121], v[134:135], v[96:97] op_sel_hi:[1,0,1]
	v_pk_fma_f32 v[118:119], v[118:119], v[134:135], v[94:95] op_sel_hi:[1,0,1]
	v_pk_fma_f32 v[116:117], v[116:117], v[134:135], v[92:93] op_sel_hi:[1,0,1]
	v_pk_fma_f32 v[114:115], v[114:115], v[134:135], v[90:91] op_sel_hi:[1,0,1]
	v_pk_fma_f32 v[112:113], v[112:113], v[134:135], v[88:89] op_sel_hi:[1,0,1]
	v_max_f32_e32 v124, 0, v124
	v_max_f32_e32 v120, 0, v120
	v_max_f32_e32 v125, 0, v125
	v_max_f32_e32 v121, 0, v121
	v_max_f32_e32 v126, 0, v126
	v_max_f32_e32 v122, 0, v122
	v_max_f32_e32 v127, 0, v127
	v_max_f32_e32 v123, 0, v123
	v_max_f32_e32 v116, 0, v116
	v_max_f32_e32 v112, 0, v112
	v_max_f32_e32 v117, 0, v117
	v_max_f32_e32 v113, 0, v113
	v_max_f32_e32 v118, 0, v118
	v_max_f32_e32 v114, 0, v114
	v_max_f32_e32 v119, 0, v119
	v_max_f32_e32 v115, 0, v115
	v_pk_mul_f32 v[124:125], v[124:125], v[124:125]
	v_pk_mul_f32 v[120:121], v[120:121], v[120:121]
	v_pk_mul_f32 v[126:127], v[126:127], v[126:127]
	v_pk_mul_f32 v[122:123], v[122:123], v[122:123]
	v_pk_mul_f32 v[116:117], v[116:117], v[116:117]
	v_pk_mul_f32 v[134:135], v[112:113], v[112:113]
	v_pk_mul_f32 v[118:119], v[118:119], v[118:119]
	v_pk_mul_f32 v[136:137], v[114:115], v[114:115]
	v_cvt_pk_bf16_f32 v112, v124, v125
	v_cvt_pk_bf16_f32 v113, v126, v127
	v_cvt_pk_bf16_f32 v114, v120, v121
	v_cvt_pk_bf16_f32 v115, v122, v123
	v_cvt_pk_bf16_f32 v116, v116, v117
	v_cvt_pk_bf16_f32 v117, v118, v119
	v_cvt_pk_bf16_f32 v118, v134, v135
	v_cvt_pk_bf16_f32 v119, v136, v137
	global_store_dwordx4 v[130:131], v[112:115], off
	global_store_dwordx4 v[130:131], v[116:119], off offset:256
	s_nop 1
	v_mov_b32_e32 v114, v231
	v_or_b32_e32 v112, 48, v164
	v_ashrrev_i32_e32 v113, 31, v112
	v_lshl_add_u64 v[116:117], v[112:113], 2, s[12:13]
	s_nop 0
	v_fmamk_f32 v114, v114, 0x3a800000, v174
	v_mul_f32_e32 v115, 0x4f800000, v114
	v_cmp_gt_f32_e32 vcc, s75, v114
	s_nop 1
	v_cndmask_b32_e32 v118, v114, v115, vcc
	v_sqrt_f32_e32 v119, v118
	v_lshlrev_b64 v[114:115], 13, v[128:129]
	v_lshl_add_u64 v[114:115], s[22:23], 0, v[114:115]
	v_lshl_add_u64 v[114:115], v[114:115], 0, v[166:167]
	v_add_u32_e32 v120, -1, v119
	v_add_u32_e32 v121, 1, v119
	v_fma_f32 v122, -v120, v119, v118
	v_fma_f32 v123, -v121, v119, v118
	v_cmp_ge_f32_e64 s[4:5], 0, v122
	s_nop 1
	v_cndmask_b32_e64 v119, v119, v120, s[4:5]
	v_cmp_lt_f32_e64 s[4:5], 0, v123
	s_nop 1
	v_cndmask_b32_e64 v119, v119, v121, s[4:5]
	v_mul_f32_e32 v120, 0x37800000, v119
	v_cndmask_b32_e32 v119, v119, v120, vcc
	v_cmp_class_f32_e32 vcc, v118, v175
	s_nop 1
	v_cndmask_b32_e32 v118, v119, v118, vcc
	v_div_scale_f32 v119, s[4:5], v118, v118, 1.0
	v_rcp_f32_e32 v120, v119
	v_div_scale_f32 v121, vcc, 1.0, v118, 1.0
	v_fma_f32 v122, -v119, v120, 1.0
	v_fmac_f32_e32 v120, v122, v120
	v_mul_f32_e32 v122, v121, v120
	v_fma_f32 v123, -v119, v122, v121
	v_fmac_f32_e32 v122, v123, v120
	v_fma_f32 v119, -v119, v122, v121
	v_div_fmas_f32 v119, v119, v120, v122
	v_div_fixup_f32 v118, v119, v118, 1.0
	v_pk_fma_f32 v[110:111], v[110:111], v[118:119], v[102:103] op_sel_hi:[1,0,1]
	v_pk_fma_f32 v[108:109], v[108:109], v[118:119], v[100:101] op_sel_hi:[1,0,1]
	v_pk_fma_f32 v[106:107], v[106:107], v[118:119], v[98:99] op_sel_hi:[1,0,1]
	v_pk_fma_f32 v[104:105], v[104:105], v[118:119], v[96:97] op_sel_hi:[1,0,1]
	v_pk_fma_f32 v[86:87], v[86:87], v[118:119], v[94:95] op_sel_hi:[1,0,1]
	v_pk_fma_f32 v[84:85], v[84:85], v[118:119], v[92:93] op_sel_hi:[1,0,1]
	v_pk_fma_f32 v[82:83], v[82:83], v[118:119], v[90:91] op_sel_hi:[1,0,1]
	v_pk_fma_f32 v[80:81], v[80:81], v[118:119], v[88:89] op_sel_hi:[1,0,1]
	v_max_f32_e32 v108, 0, v108
	v_max_f32_e32 v104, 0, v104
	v_max_f32_e32 v109, 0, v109
	v_max_f32_e32 v105, 0, v105
	v_max_f32_e32 v110, 0, v110
	v_max_f32_e32 v106, 0, v106
	v_max_f32_e32 v111, 0, v111
	v_max_f32_e32 v107, 0, v107
	v_max_f32_e32 v84, 0, v84
	v_max_f32_e32 v80, 0, v80
	v_max_f32_e32 v85, 0, v85
	v_max_f32_e32 v81, 0, v81
	v_max_f32_e32 v86, 0, v86
	v_max_f32_e32 v82, 0, v82
	v_max_f32_e32 v87, 0, v87
	v_max_f32_e32 v83, 0, v83
	v_pk_mul_f32 v[108:109], v[108:109], v[108:109]
	v_pk_mul_f32 v[104:105], v[104:105], v[104:105]
	v_pk_mul_f32 v[110:111], v[110:111], v[110:111]
	v_pk_mul_f32 v[106:107], v[106:107], v[106:107]
	v_pk_mul_f32 v[84:85], v[84:85], v[84:85]
	v_pk_mul_f32 v[118:119], v[80:81], v[80:81]
	v_pk_mul_f32 v[86:87], v[86:87], v[86:87]
	v_pk_mul_f32 v[120:121], v[82:83], v[82:83]
	v_cvt_pk_bf16_f32 v80, v108, v109
	v_cvt_pk_bf16_f32 v81, v110, v111
	v_cvt_pk_bf16_f32 v82, v104, v105
	v_cvt_pk_bf16_f32 v83, v106, v107
	v_cvt_pk_bf16_f32 v84, v84, v85
	v_cvt_pk_bf16_f32 v85, v86, v87
	v_cvt_pk_bf16_f32 v86, v118, v119
	v_cvt_pk_bf16_f32 v87, v120, v121
	global_store_dwordx4 v[114:115], v[80:83], off
	global_store_dwordx4 v[114:115], v[84:87], off offset:256
	s_nop 1
	v_mov_b32_e32 v80, v232
	s_nop 0
	v_fmamk_f32 v80, v80, 0x3a800000, v174
	v_mul_f32_e32 v81, 0x4f800000, v80
	v_cmp_gt_f32_e32 vcc, s75, v80
	s_nop 1
	v_cndmask_b32_e32 v82, v80, v81, vcc
	v_sqrt_f32_e32 v83, v82
	v_lshlrev_b64 v[80:81], 13, v[112:113]
	v_lshl_add_u64 v[80:81], s[22:23], 0, v[80:81]
	v_lshl_add_u64 v[80:81], v[80:81], 0, v[166:167]
	v_add_u32_e32 v84, -1, v83
	v_add_u32_e32 v85, 1, v83
	v_fma_f32 v86, -v84, v83, v82
	v_fma_f32 v87, -v85, v83, v82
	v_cmp_ge_f32_e64 s[4:5], 0, v86
	s_nop 1
	v_cndmask_b32_e64 v83, v83, v84, s[4:5]
	v_cmp_lt_f32_e64 s[4:5], 0, v87
	s_nop 1
	v_cndmask_b32_e64 v83, v83, v85, s[4:5]
	v_mul_f32_e32 v84, 0x37800000, v83
	v_cndmask_b32_e32 v83, v83, v84, vcc
	v_cmp_class_f32_e32 vcc, v82, v175
	s_nop 1
	v_cndmask_b32_e32 v82, v83, v82, vcc
	v_div_scale_f32 v83, s[4:5], v82, v82, 1.0
	v_rcp_f32_e32 v84, v83
	v_div_scale_f32 v85, vcc, 1.0, v82, 1.0
	v_fma_f32 v86, -v83, v84, 1.0
	v_fmac_f32_e32 v84, v86, v84
	v_mul_f32_e32 v86, v85, v84
	v_fma_f32 v87, -v83, v86, v85
	v_fmac_f32_e32 v86, v87, v84
	v_fma_f32 v83, -v83, v86, v85
	v_div_fmas_f32 v83, v83, v84, v86
	v_div_fixup_f32 v82, v83, v82, 1.0
	v_pk_fma_f32 v[78:79], v[78:79], v[82:83], v[102:103] op_sel_hi:[1,0,1]
	v_pk_fma_f32 v[76:77], v[76:77], v[82:83], v[100:101] op_sel_hi:[1,0,1]
	v_pk_fma_f32 v[74:75], v[74:75], v[82:83], v[98:99] op_sel_hi:[1,0,1]
	v_pk_fma_f32 v[72:73], v[72:73], v[82:83], v[96:97] op_sel_hi:[1,0,1]
	v_pk_fma_f32 v[70:71], v[70:71], v[82:83], v[94:95] op_sel_hi:[1,0,1]
	v_pk_fma_f32 v[68:69], v[68:69], v[82:83], v[92:93] op_sel_hi:[1,0,1]
	v_pk_fma_f32 v[66:67], v[66:67], v[82:83], v[90:91] op_sel_hi:[1,0,1]
	v_pk_fma_f32 v[64:65], v[64:65], v[82:83], v[88:89] op_sel_hi:[1,0,1]
	v_max_f32_e32 v76, 0, v76
	v_max_f32_e32 v72, 0, v72
	v_max_f32_e32 v77, 0, v77
	v_max_f32_e32 v73, 0, v73
	v_max_f32_e32 v78, 0, v78
	v_max_f32_e32 v74, 0, v74
	v_max_f32_e32 v79, 0, v79
	v_max_f32_e32 v75, 0, v75
	v_max_f32_e32 v68, 0, v68
	v_max_f32_e32 v64, 0, v64
	v_max_f32_e32 v69, 0, v69
	v_max_f32_e32 v65, 0, v65
	v_max_f32_e32 v70, 0, v70
	v_max_f32_e32 v66, 0, v66
	v_max_f32_e32 v71, 0, v71
	v_max_f32_e32 v67, 0, v67
	v_pk_mul_f32 v[76:77], v[76:77], v[76:77]
	v_pk_mul_f32 v[72:73], v[72:73], v[72:73]
	v_pk_mul_f32 v[78:79], v[78:79], v[78:79]
	v_pk_mul_f32 v[74:75], v[74:75], v[74:75]
	v_pk_mul_f32 v[68:69], v[68:69], v[68:69]
	v_pk_mul_f32 v[82:83], v[64:65], v[64:65]
	v_pk_mul_f32 v[70:71], v[70:71], v[70:71]
	v_pk_mul_f32 v[84:85], v[66:67], v[66:67]
	v_cvt_pk_bf16_f32 v64, v76, v77
	v_cvt_pk_bf16_f32 v65, v78, v79
	v_cvt_pk_bf16_f32 v66, v72, v73
	v_cvt_pk_bf16_f32 v67, v74, v75
	v_cvt_pk_bf16_f32 v68, v68, v69
	v_cvt_pk_bf16_f32 v69, v70, v71
	v_cvt_pk_bf16_f32 v70, v82, v83
	v_cvt_pk_bf16_f32 v71, v84, v85
	global_store_dwordx4 v[80:81], v[64:67], off
	global_store_dwordx4 v[80:81], v[68:71], off offset:256
	s_nop 1
	v_mov_b32_e32 v64, v233
	s_nop 0
	v_fmamk_f32 v64, v64, 0x3a800000, v174
	v_mul_f32_e32 v65, 0x4f800000, v64
	v_cmp_gt_f32_e32 vcc, s75, v64
	s_nop 1
	v_cndmask_b32_e32 v66, v64, v65, vcc
	v_sqrt_f32_e32 v67, v66
	v_lshl_add_u64 v[64:65], v[162:163], 0, s[20:21]
	v_add_u32_e32 v68, -1, v67
	v_add_u32_e32 v69, 1, v67
	v_fma_f32 v70, -v68, v67, v66
	v_fma_f32 v71, -v69, v67, v66
	v_cmp_ge_f32_e64 s[4:5], 0, v70
	s_nop 1
	v_cndmask_b32_e64 v67, v67, v68, s[4:5]
	v_cmp_lt_f32_e64 s[4:5], 0, v71
	s_nop 1
	v_cndmask_b32_e64 v67, v67, v69, s[4:5]
	v_mul_f32_e32 v68, 0x37800000, v67
	v_cndmask_b32_e32 v67, v67, v68, vcc
	v_cmp_class_f32_e32 vcc, v66, v175
	s_nop 1
	v_cndmask_b32_e32 v68, v67, v66, vcc
	v_div_scale_f32 v69, s[4:5], v68, v68, 1.0
	v_rcp_f32_e32 v70, v69
	v_add_co_u32_e32 v66, vcc, s76, v162
	v_fma_f32 v72, -v69, v70, 1.0
	s_nop 0
	v_addc_co_u32_e32 v67, vcc, 0, v163, vcc
	v_div_scale_f32 v71, vcc, 1.0, v68, 1.0
	v_fmac_f32_e32 v70, v72, v70
	v_mul_f32_e32 v72, v71, v70
	v_fma_f32 v73, -v69, v72, v71
	v_fmac_f32_e32 v72, v73, v70
	v_fma_f32 v69, -v69, v72, v71
	v_div_fmas_f32 v69, v69, v70, v72
	v_div_fixup_f32 v68, v69, v68, 1.0
	v_pk_fma_f32 v[62:63], v[62:63], v[68:69], v[102:103] op_sel_hi:[1,0,1]
	v_pk_fma_f32 v[60:61], v[60:61], v[68:69], v[100:101] op_sel_hi:[1,0,1]
	v_pk_fma_f32 v[58:59], v[58:59], v[68:69], v[98:99] op_sel_hi:[1,0,1]
	v_pk_fma_f32 v[56:57], v[56:57], v[68:69], v[96:97] op_sel_hi:[1,0,1]
	v_pk_fma_f32 v[54:55], v[54:55], v[68:69], v[94:95] op_sel_hi:[1,0,1]
	v_pk_fma_f32 v[52:53], v[52:53], v[68:69], v[92:93] op_sel_hi:[1,0,1]
	v_pk_fma_f32 v[50:51], v[50:51], v[68:69], v[90:91] op_sel_hi:[1,0,1]
	v_pk_fma_f32 v[48:49], v[48:49], v[68:69], v[88:89] op_sel_hi:[1,0,1]
	v_max_f32_e32 v60, 0, v60
	v_max_f32_e32 v56, 0, v56
	v_max_f32_e32 v61, 0, v61
	v_max_f32_e32 v57, 0, v57
	v_max_f32_e32 v62, 0, v62
	v_max_f32_e32 v58, 0, v58
	v_max_f32_e32 v63, 0, v63
	v_max_f32_e32 v59, 0, v59
	v_max_f32_e32 v52, 0, v52
	v_max_f32_e32 v48, 0, v48
	v_max_f32_e32 v53, 0, v53
	v_max_f32_e32 v49, 0, v49
	v_max_f32_e32 v54, 0, v54
	v_max_f32_e32 v50, 0, v50
	v_max_f32_e32 v55, 0, v55
	v_max_f32_e32 v51, 0, v51
	v_pk_mul_f32 v[60:61], v[60:61], v[60:61]
	v_pk_mul_f32 v[56:57], v[56:57], v[56:57]
	v_pk_mul_f32 v[62:63], v[62:63], v[62:63]
	v_pk_mul_f32 v[58:59], v[58:59], v[58:59]
	v_pk_mul_f32 v[52:53], v[52:53], v[52:53]
	v_pk_mul_f32 v[68:69], v[48:49], v[48:49]
	v_pk_mul_f32 v[54:55], v[54:55], v[54:55]
	v_pk_mul_f32 v[70:71], v[50:51], v[50:51]
	v_cvt_pk_bf16_f32 v48, v60, v61
	v_cvt_pk_bf16_f32 v49, v62, v63
	v_cvt_pk_bf16_f32 v50, v56, v57
	v_cvt_pk_bf16_f32 v51, v58, v59
	v_cvt_pk_bf16_f32 v52, v52, v53
	v_cvt_pk_bf16_f32 v53, v54, v55
	v_cvt_pk_bf16_f32 v54, v68, v69
	v_cvt_pk_bf16_f32 v55, v70, v71
	global_store_dwordx4 v[66:67], v[48:51], off
	global_store_dwordx4 v[64:65], v[52:55], off offset:256
	s_nop 1
	v_mov_b32_e32 v48, v234
	s_nop 0
	v_fmamk_f32 v48, v48, 0x3a800000, v174
	v_mul_f32_e32 v49, 0x4f800000, v48
	v_cmp_gt_f32_e32 vcc, s75, v48
	s_nop 1
	v_cndmask_b32_e32 v50, v48, v49, vcc
	v_sqrt_f32_e32 v51, v50
	v_lshl_add_u64 v[48:49], v[162:163], 0, s[24:25]
	v_add_u32_e32 v52, -1, v51
	v_add_u32_e32 v53, 1, v51
	v_fma_f32 v54, -v52, v51, v50
	v_fma_f32 v55, -v53, v51, v50
	v_cmp_ge_f32_e64 s[4:5], 0, v54
	s_nop 1
	v_cndmask_b32_e64 v51, v51, v52, s[4:5]
	v_cmp_lt_f32_e64 s[4:5], 0, v55
	s_nop 1
	v_cndmask_b32_e64 v51, v51, v53, s[4:5]
	v_mul_f32_e32 v52, 0x37800000, v51
	v_cndmask_b32_e32 v51, v51, v52, vcc
	v_cmp_class_f32_e32 vcc, v50, v175
	s_nop 1
	v_cndmask_b32_e32 v52, v51, v50, vcc
	v_div_scale_f32 v53, s[4:5], v52, v52, 1.0
	v_rcp_f32_e32 v54, v53
	v_add_co_u32_e32 v50, vcc, s77, v162
	v_fma_f32 v56, -v53, v54, 1.0
	s_nop 0
	v_addc_co_u32_e32 v51, vcc, 0, v163, vcc
	v_div_scale_f32 v55, vcc, 1.0, v52, 1.0
	v_fmac_f32_e32 v54, v56, v54
	v_mul_f32_e32 v56, v55, v54
	v_fma_f32 v57, -v53, v56, v55
	v_fmac_f32_e32 v56, v57, v54
	v_fma_f32 v53, -v53, v56, v55
	v_div_fmas_f32 v53, v53, v54, v56
	v_div_fixup_f32 v52, v53, v52, 1.0
	v_pk_fma_f32 v[46:47], v[46:47], v[52:53], v[102:103] op_sel_hi:[1,0,1]
	v_pk_fma_f32 v[44:45], v[44:45], v[52:53], v[100:101] op_sel_hi:[1,0,1]
	v_pk_fma_f32 v[42:43], v[42:43], v[52:53], v[98:99] op_sel_hi:[1,0,1]
	v_pk_fma_f32 v[40:41], v[40:41], v[52:53], v[96:97] op_sel_hi:[1,0,1]
	v_pk_fma_f32 v[38:39], v[38:39], v[52:53], v[94:95] op_sel_hi:[1,0,1]
	v_pk_fma_f32 v[36:37], v[36:37], v[52:53], v[92:93] op_sel_hi:[1,0,1]
	v_pk_fma_f32 v[34:35], v[34:35], v[52:53], v[90:91] op_sel_hi:[1,0,1]
	v_pk_fma_f32 v[32:33], v[32:33], v[52:53], v[88:89] op_sel_hi:[1,0,1]
	v_max_f32_e32 v44, 0, v44
	v_max_f32_e32 v40, 0, v40
	v_max_f32_e32 v45, 0, v45
	v_max_f32_e32 v41, 0, v41
	v_max_f32_e32 v46, 0, v46
	v_max_f32_e32 v42, 0, v42
	v_max_f32_e32 v47, 0, v47
	v_max_f32_e32 v43, 0, v43
	v_max_f32_e32 v36, 0, v36
	v_max_f32_e32 v32, 0, v32
	v_max_f32_e32 v37, 0, v37
	v_max_f32_e32 v33, 0, v33
	v_max_f32_e32 v38, 0, v38
	v_max_f32_e32 v34, 0, v34
	v_max_f32_e32 v39, 0, v39
	v_max_f32_e32 v35, 0, v35
	v_pk_mul_f32 v[44:45], v[44:45], v[44:45]
	v_pk_mul_f32 v[40:41], v[40:41], v[40:41]
	v_pk_mul_f32 v[46:47], v[46:47], v[46:47]
	v_pk_mul_f32 v[42:43], v[42:43], v[42:43]
	v_pk_mul_f32 v[36:37], v[36:37], v[36:37]
	v_pk_mul_f32 v[52:53], v[32:33], v[32:33]
	v_pk_mul_f32 v[38:39], v[38:39], v[38:39]
	v_pk_mul_f32 v[54:55], v[34:35], v[34:35]
	v_cvt_pk_bf16_f32 v32, v44, v45
	v_cvt_pk_bf16_f32 v33, v46, v47
	v_cvt_pk_bf16_f32 v34, v40, v41
	v_cvt_pk_bf16_f32 v35, v42, v43
	v_cvt_pk_bf16_f32 v36, v36, v37
	v_cvt_pk_bf16_f32 v37, v38, v39
	v_cvt_pk_bf16_f32 v38, v52, v53
	v_cvt_pk_bf16_f32 v39, v54, v55
	global_store_dwordx4 v[50:51], v[32:35], off
	global_store_dwordx4 v[48:49], v[36:39], off offset:256
	s_nop 1
	v_mov_b32_e32 v32, v235
	s_nop 0
	v_fmamk_f32 v32, v32, 0x3a800000, v174
	v_mul_f32_e32 v33, 0x4f800000, v32
	v_cmp_gt_f32_e32 vcc, s75, v32
	s_nop 1
	v_cndmask_b32_e32 v34, v32, v33, vcc
	v_sqrt_f32_e32 v35, v34
	v_lshl_add_u64 v[32:33], v[162:163], 0, s[26:27]
	v_add_u32_e32 v36, -1, v35
	v_add_u32_e32 v37, 1, v35
	v_fma_f32 v38, -v36, v35, v34
	v_fma_f32 v39, -v37, v35, v34
	v_cmp_ge_f32_e64 s[4:5], 0, v38
	s_nop 1
	v_cndmask_b32_e64 v35, v35, v36, s[4:5]
	v_cmp_lt_f32_e64 s[4:5], 0, v39
	s_nop 1
	v_cndmask_b32_e64 v35, v35, v37, s[4:5]
	v_mul_f32_e32 v36, 0x37800000, v35
	v_cndmask_b32_e32 v35, v35, v36, vcc
	v_cmp_class_f32_e32 vcc, v34, v175
	s_nop 1
	v_cndmask_b32_e32 v36, v35, v34, vcc
	v_div_scale_f32 v37, s[4:5], v36, v36, 1.0
	v_rcp_f32_e32 v38, v37
	v_add_co_u32_e32 v34, vcc, s78, v162
	v_fma_f32 v40, -v37, v38, 1.0
	s_nop 0
	v_addc_co_u32_e32 v35, vcc, 0, v163, vcc
	v_div_scale_f32 v39, vcc, 1.0, v36, 1.0
	v_fmac_f32_e32 v38, v40, v38
	v_mul_f32_e32 v40, v39, v38
	v_fma_f32 v41, -v37, v40, v39
	v_fmac_f32_e32 v40, v41, v38
	v_fma_f32 v37, -v37, v40, v39
	v_div_fmas_f32 v37, v37, v38, v40
	v_div_fixup_f32 v36, v37, v36, 1.0
	v_pk_fma_f32 v[30:31], v[30:31], v[36:37], v[102:103] op_sel_hi:[1,0,1]
	v_pk_fma_f32 v[28:29], v[28:29], v[36:37], v[100:101] op_sel_hi:[1,0,1]
	v_pk_fma_f32 v[26:27], v[26:27], v[36:37], v[98:99] op_sel_hi:[1,0,1]
	v_pk_fma_f32 v[24:25], v[24:25], v[36:37], v[96:97] op_sel_hi:[1,0,1]
	v_pk_fma_f32 v[22:23], v[22:23], v[36:37], v[94:95] op_sel_hi:[1,0,1]
	v_pk_fma_f32 v[20:21], v[20:21], v[36:37], v[92:93] op_sel_hi:[1,0,1]
	v_pk_fma_f32 v[18:19], v[18:19], v[36:37], v[90:91] op_sel_hi:[1,0,1]
	v_pk_fma_f32 v[16:17], v[16:17], v[36:37], v[88:89] op_sel_hi:[1,0,1]
	v_max_f32_e32 v28, 0, v28
	v_max_f32_e32 v24, 0, v24
	v_max_f32_e32 v29, 0, v29
	v_max_f32_e32 v25, 0, v25
	v_max_f32_e32 v30, 0, v30
	v_max_f32_e32 v26, 0, v26
	v_max_f32_e32 v31, 0, v31
	v_max_f32_e32 v27, 0, v27
	v_max_f32_e32 v20, 0, v20
	v_max_f32_e32 v16, 0, v16
	v_max_f32_e32 v21, 0, v21
	v_max_f32_e32 v17, 0, v17
	v_max_f32_e32 v22, 0, v22
	v_max_f32_e32 v18, 0, v18
	v_max_f32_e32 v23, 0, v23
	v_max_f32_e32 v19, 0, v19
	v_pk_mul_f32 v[28:29], v[28:29], v[28:29]
	v_pk_mul_f32 v[24:25], v[24:25], v[24:25]
	v_pk_mul_f32 v[30:31], v[30:31], v[30:31]
	v_pk_mul_f32 v[26:27], v[26:27], v[26:27]
	v_pk_mul_f32 v[20:21], v[20:21], v[20:21]
	v_pk_mul_f32 v[36:37], v[16:17], v[16:17]
	v_pk_mul_f32 v[22:23], v[22:23], v[22:23]
	v_pk_mul_f32 v[38:39], v[18:19], v[18:19]
	v_cvt_pk_bf16_f32 v16, v28, v29
	v_cvt_pk_bf16_f32 v17, v30, v31
	v_cvt_pk_bf16_f32 v18, v24, v25
	v_cvt_pk_bf16_f32 v19, v26, v27
	v_cvt_pk_bf16_f32 v20, v20, v21
	v_cvt_pk_bf16_f32 v21, v22, v23
	v_cvt_pk_bf16_f32 v22, v36, v37
	v_cvt_pk_bf16_f32 v23, v38, v39
	global_store_dwordx4 v[34:35], v[16:19], off
	global_store_dwordx4 v[32:33], v[20:23], off offset:256
	s_nop 1
	v_mov_b32_e32 v16, v236
	s_nop 0
	v_fmamk_f32 v16, v16, 0x3a800000, v174
	v_mul_f32_e32 v17, 0x4f800000, v16
	v_cmp_gt_f32_e32 vcc, s75, v16
	s_nop 1
	v_cndmask_b32_e32 v18, v16, v17, vcc
	v_sqrt_f32_e32 v19, v18
	v_lshl_add_u64 v[16:17], v[162:163], 0, s[28:29]
	v_add_u32_e32 v20, -1, v19
	v_add_u32_e32 v21, 1, v19
	v_fma_f32 v22, -v20, v19, v18
	v_fma_f32 v23, -v21, v19, v18
	v_cmp_ge_f32_e64 s[4:5], 0, v22
	s_nop 1
	v_cndmask_b32_e64 v19, v19, v20, s[4:5]
	v_cmp_lt_f32_e64 s[4:5], 0, v23
	s_nop 1
	v_cndmask_b32_e64 v19, v19, v21, s[4:5]
	v_mul_f32_e32 v20, 0x37800000, v19
	v_cndmask_b32_e32 v19, v19, v20, vcc
	v_cmp_class_f32_e32 vcc, v18, v175
	s_nop 1
	v_cndmask_b32_e32 v20, v19, v18, vcc
	v_div_scale_f32 v21, s[4:5], v20, v20, 1.0
	v_rcp_f32_e32 v22, v21
	v_add_co_u32_e32 v18, vcc, s79, v162
	v_fma_f32 v24, -v21, v22, 1.0
	s_nop 0
	v_addc_co_u32_e32 v19, vcc, 0, v163, vcc
	v_div_scale_f32 v23, vcc, 1.0, v20, 1.0
	v_fmac_f32_e32 v22, v24, v22
	v_mul_f32_e32 v24, v23, v22
	v_fma_f32 v25, -v21, v24, v23
	v_fmac_f32_e32 v24, v25, v22
	v_fma_f32 v21, -v21, v24, v23
	v_div_fmas_f32 v21, v21, v22, v24
	v_div_fixup_f32 v20, v21, v20, 1.0
	v_pk_fma_f32 v[14:15], v[14:15], v[20:21], v[102:103] op_sel_hi:[1,0,1]
	v_pk_fma_f32 v[12:13], v[12:13], v[20:21], v[100:101] op_sel_hi:[1,0,1]
	v_pk_fma_f32 v[10:11], v[10:11], v[20:21], v[98:99] op_sel_hi:[1,0,1]
	v_pk_fma_f32 v[8:9], v[8:9], v[20:21], v[96:97] op_sel_hi:[1,0,1]
	v_pk_fma_f32 v[6:7], v[6:7], v[20:21], v[94:95] op_sel_hi:[1,0,1]
	v_pk_fma_f32 v[4:5], v[4:5], v[20:21], v[92:93] op_sel_hi:[1,0,1]
	v_pk_fma_f32 v[2:3], v[2:3], v[20:21], v[90:91] op_sel_hi:[1,0,1]
	v_pk_fma_f32 v[0:1], v[0:1], v[20:21], v[88:89] op_sel_hi:[1,0,1]
	v_max_f32_e32 v12, 0, v12
	v_max_f32_e32 v8, 0, v8
	v_max_f32_e32 v13, 0, v13
	v_max_f32_e32 v9, 0, v9
	v_max_f32_e32 v14, 0, v14
	v_max_f32_e32 v10, 0, v10
	v_max_f32_e32 v15, 0, v15
	v_max_f32_e32 v11, 0, v11
	v_max_f32_e32 v4, 0, v4
	v_max_f32_e32 v0, 0, v0
	v_max_f32_e32 v5, 0, v5
	v_max_f32_e32 v1, 0, v1
	v_max_f32_e32 v6, 0, v6
	v_max_f32_e32 v2, 0, v2
	v_max_f32_e32 v7, 0, v7
	v_max_f32_e32 v3, 0, v3
	v_pk_mul_f32 v[12:13], v[12:13], v[12:13]
	v_pk_mul_f32 v[8:9], v[8:9], v[8:9]
	v_pk_mul_f32 v[14:15], v[14:15], v[14:15]
	v_pk_mul_f32 v[10:11], v[10:11], v[10:11]
	s_andn2_b64 vcc, exec, s[0:1]
	v_pk_mul_f32 v[4:5], v[4:5], v[4:5]
	v_pk_mul_f32 v[20:21], v[0:1], v[0:1]
	v_pk_mul_f32 v[6:7], v[6:7], v[6:7]
	v_pk_mul_f32 v[22:23], v[2:3], v[2:3]
	v_cvt_pk_bf16_f32 v0, v12, v13
	v_cvt_pk_bf16_f32 v1, v14, v15
	v_cvt_pk_bf16_f32 v2, v8, v9
	v_cvt_pk_bf16_f32 v3, v10, v11
	s_mov_b64 s[0:1], -1
	v_cvt_pk_bf16_f32 v4, v4, v5
	v_cvt_pk_bf16_f32 v5, v6, v7
	v_cvt_pk_bf16_f32 v6, v20, v21
	v_cvt_pk_bf16_f32 v7, v22, v23
	global_store_dwordx4 v[18:19], v[0:3], off
	global_store_dwordx4 v[16:17], v[4:7], off offset:256
	s_cbranch_vccnz .LBB0_745
	s_andn2_b64 vcc, exec, s[8:9]
	s_cbranch_vccnz .LBB0_744
	s_barrier
	s_branch .LBB0_744
